# s5_out Toeplitz loops software-pipelined (LDS reads one trip ahead, mask only in the final trip); P1 epilogue rope-wave wait count
# speedup vs baseline: 1.0065x; 1.0041x over previous
;     __device__ __forceinline__ float apply(int row, int col, float (&v)[8], const Pre& p) const {
;         const float r = p.r;
; #pragma unroll
;         for (int i = 0; i < 8; ++i) v[i] *= r;
;         const int reg = col >> 10, c = col & 1023;
;         bf16* dst;
;         if (reg < 2) {
;             if ((c & 127) < 32) {
; #pragma unroll
;                 for (int i = 0; i < 4; ++i) { const float x1 = v[i], x2 = v[4 + i]; v[i] = x1 * p.cs[i] - x2 * p.sn[i]; v[4 + i] = x2 * p.cs[i] + x1 * p.sn[i]; }
;             }
;             if (reg == 0) {
; #pragma unroll
;                 for (int i = 0; i < 8; ++i) v[i] *= QSCALE;
;             }
;             dst = (reg == 0 ? Q : K) + (size_t)row * 1024 + c;
;         } else if (reg == 2) dst = V + (size_t)row * 1024 + c;
;         else dst = U + ((size_t)(c >> 4) * S + row) * 16 + (c & 15);
.LBB0_354:
	s_or_b64 exec, exec, s[2:3]
	v_lshlrev_b64 v[132:133], 11, v[144:145]
	s_and_b64 s[100:101], s[44:45], s[46:47]
	s_cbranch_scc0 .Lp1w3_0
	s_waitcnt vmcnt(7)
	s_branch .Lp1wj_0
.Lp1w3_0:
	s_waitcnt vmcnt(3)
.Lp1wj_0:
	v_pk_mul_f32 v[134:135], v[124:125], v[146:147] op_sel_hi:[1,0]
	v_pk_mul_f32 v[120:121], v[120:121], v[146:147] op_sel_hi:[1,0]
	v_pk_mul_f32 v[124:125], v[126:127], v[146:147] op_sel_hi:[1,0]
	v_pk_mul_f32 v[122:123], v[122:123], v[146:147] op_sel_hi:[1,0]
	s_and_b64 vcc, exec, s[10:11]
	s_mov_b64 s[2:3], -1
	s_cbranch_vccnz .LBB0_360
	s_and_b64 vcc, exec, s[8:9]
	s_cbranch_vccnz .LBB0_357
	v_lshlrev_b32_e32 v126, 10, v207
	v_and_b32_e32 v168, 0xdc000, v126
	v_lshl_add_u64 v[126:127], v[168:169], 0, v[144:145]
	v_lshlrev_b64 v[126:127], 5, v[126:127]
	v_lshl_add_u64 v[126:127], s[86:87], 0, v[126:127]
	v_mov_b32_e32 v168, v203
	s_cbranch_execz .LBB0_358
	s_branch .LBB0_359

;     __device__ __forceinline__ float apply(int row, int col, float (&v)[8], const Pre& p) const {
;         const float r = p.r;
; #pragma unroll
;         for (int i = 0; i < 8; ++i) v[i] *= r;
.LBB0_380:
	s_or_b64 exec, exec, s[2:3]
	v_lshlrev_b64 v[116:117], 11, v[128:129]
	s_and_b64 s[100:101], s[44:45], s[46:47]
	s_cbranch_scc0 .Lp1w3_1
	s_waitcnt vmcnt(7)
	s_branch .Lp1wj_1

;     __device__ __forceinline__ float apply(int row, int col, float (&v)[8], const Pre& p) const {
;         const float r = p.r;
; #pragma unroll
;         for (int i = 0; i < 8; ++i) v[i] *= r;
;         const int reg = col >> 10, c = col & 1023;
;         bf16* dst;
;         if (reg < 2) {
;             if ((c & 127) < 32) {
; #pragma unroll
;                 for (int i = 0; i < 4; ++i) { const float x1 = v[i], x2 = v[4 + i]; v[i] = x1 * p.cs[i] - x2 * p.sn[i]; v[4 + i] = x2 * p.cs[i] + x1 * p.sn[i]; }
;             }
;             if (reg == 0) {
; #pragma unroll
;                 for (int i = 0; i < 8; ++i) v[i] *= QSCALE;
;             }
;             dst = (reg == 0 ? Q : K) + (size_t)row * 1024 + c;
;         } else if (reg == 2) dst = V + (size_t)row * 1024 + c;
;         else dst = U + ((size_t)(c >> 4) * S + row) * 16 + (c & 15);
.Lp1wj_1:
	v_pk_mul_f32 v[118:119], v[108:109], v[130:131] op_sel_hi:[1,0]
	v_pk_mul_f32 v[104:105], v[104:105], v[130:131] op_sel_hi:[1,0]
	v_pk_mul_f32 v[108:109], v[110:111], v[130:131] op_sel_hi:[1,0]
	v_pk_mul_f32 v[106:107], v[106:107], v[130:131] op_sel_hi:[1,0]
	s_and_b64 vcc, exec, s[10:11]
	s_mov_b64 s[2:3], -1
	s_cbranch_vccnz .LBB0_386
	s_and_b64 vcc, exec, s[8:9]
	s_cbranch_vccnz .LBB0_383
	v_lshlrev_b32_e32 v110, 10, v207
	v_and_b32_e32 v168, 0xdc000, v110
	v_lshl_add_u64 v[110:111], v[168:169], 0, v[128:129]
	v_lshlrev_b64 v[110:111], 5, v[110:111]
	v_lshl_add_u64 v[110:111], s[86:87], 0, v[110:111]
	v_mov_b32_e32 v168, v203
	s_cbranch_execz .LBB0_384
	s_branch .LBB0_385

;     __device__ __forceinline__ float apply(int row, int col, float (&v)[8], const Pre& p) const {
;         const float r = p.r;
; #pragma unroll
;         for (int i = 0; i < 8; ++i) v[i] *= r;
.LBB0_406:
	s_or_b64 exec, exec, s[2:3]
	v_lshlrev_b64 v[100:101], 11, v[112:113]
	s_and_b64 s[100:101], s[44:45], s[46:47]
	s_cbranch_scc0 .Lp1w3_2
	s_waitcnt vmcnt(7)
	s_branch .Lp1wj_2

;     __device__ __forceinline__ float apply(int row, int col, float (&v)[8], const Pre& p) const {
;         const float r = p.r;
; #pragma unroll
;         for (int i = 0; i < 8; ++i) v[i] *= r;
;         const int reg = col >> 10, c = col & 1023;
;         bf16* dst;
;         if (reg < 2) {
;             if ((c & 127) < 32) {
; #pragma unroll
;                 for (int i = 0; i < 4; ++i) { const float x1 = v[i], x2 = v[4 + i]; v[i] = x1 * p.cs[i] - x2 * p.sn[i]; v[4 + i] = x2 * p.cs[i] + x1 * p.sn[i]; }
;             }
;             if (reg == 0) {
; #pragma unroll
;                 for (int i = 0; i < 8; ++i) v[i] *= QSCALE;
;             }
;             dst = (reg == 0 ? Q : K) + (size_t)row * 1024 + c;
;         } else if (reg == 2) dst = V + (size_t)row * 1024 + c;
;         else dst = U + ((size_t)(c >> 4) * S + row) * 16 + (c & 15);
.Lp1wj_2:
	v_pk_mul_f32 v[102:103], v[92:93], v[114:115] op_sel_hi:[1,0]
	v_pk_mul_f32 v[88:89], v[88:89], v[114:115] op_sel_hi:[1,0]
	v_pk_mul_f32 v[92:93], v[94:95], v[114:115] op_sel_hi:[1,0]
	v_pk_mul_f32 v[90:91], v[90:91], v[114:115] op_sel_hi:[1,0]
	s_and_b64 vcc, exec, s[10:11]
	s_mov_b64 s[2:3], -1
	s_cbranch_vccnz .LBB0_412
	s_and_b64 vcc, exec, s[8:9]
	s_cbranch_vccnz .LBB0_409
	v_lshlrev_b32_e32 v94, 10, v207
	v_and_b32_e32 v168, 0xdc000, v94
	v_lshl_add_u64 v[94:95], v[168:169], 0, v[112:113]
	v_lshlrev_b64 v[94:95], 5, v[94:95]
	v_lshl_add_u64 v[94:95], s[86:87], 0, v[94:95]
	v_mov_b32_e32 v168, v203
	s_cbranch_execz .LBB0_410
	s_branch .LBB0_411

;     __device__ __forceinline__ float apply(int row, int col, float (&v)[8], const Pre& p) const {
;         const float r = p.r;
; #pragma unroll
;         for (int i = 0; i < 8; ++i) v[i] *= r;
.LBB0_432:
	s_or_b64 exec, exec, s[2:3]
	v_lshlrev_b64 v[84:85], 11, v[96:97]
	s_and_b64 s[100:101], s[44:45], s[46:47]
	s_cbranch_scc0 .Lp1w3_3
	s_waitcnt vmcnt(7)
	s_branch .Lp1wj_3

;     __device__ __forceinline__ float apply(int row, int col, float (&v)[8], const Pre& p) const {
;         const float r = p.r;
; #pragma unroll
;         for (int i = 0; i < 8; ++i) v[i] *= r;
;         const int reg = col >> 10, c = col & 1023;
;         bf16* dst;
;         if (reg < 2) {
;             if ((c & 127) < 32) {
; #pragma unroll
;                 for (int i = 0; i < 4; ++i) { const float x1 = v[i], x2 = v[4 + i]; v[i] = x1 * p.cs[i] - x2 * p.sn[i]; v[4 + i] = x2 * p.cs[i] + x1 * p.sn[i]; }
;             }
;             if (reg == 0) {
; #pragma unroll
;                 for (int i = 0; i < 8; ++i) v[i] *= QSCALE;
;             }
;             dst = (reg == 0 ? Q : K) + (size_t)row * 1024 + c;
;         } else if (reg == 2) dst = V + (size_t)row * 1024 + c;
;         else dst = U + ((size_t)(c >> 4) * S + row) * 16 + (c & 15);
.Lp1wj_3:
	v_pk_mul_f32 v[86:87], v[68:69], v[98:99] op_sel_hi:[1,0]
	v_pk_mul_f32 v[64:65], v[64:65], v[98:99] op_sel_hi:[1,0]
	v_pk_mul_f32 v[68:69], v[70:71], v[98:99] op_sel_hi:[1,0]
	v_pk_mul_f32 v[66:67], v[66:67], v[98:99] op_sel_hi:[1,0]
	s_and_b64 vcc, exec, s[10:11]
	s_mov_b64 s[2:3], -1
	s_cbranch_vccnz .LBB0_438
	s_and_b64 vcc, exec, s[8:9]
	s_cbranch_vccnz .LBB0_435
	v_lshlrev_b32_e32 v70, 10, v207
	v_and_b32_e32 v168, 0xdc000, v70
	v_lshl_add_u64 v[70:71], v[168:169], 0, v[96:97]
	v_lshlrev_b64 v[70:71], 5, v[70:71]
	v_lshl_add_u64 v[70:71], s[86:87], 0, v[70:71]
	v_mov_b32_e32 v168, v203
	s_cbranch_execz .LBB0_436
	s_branch .LBB0_437

;     __device__ __forceinline__ float apply(int row, int col, float (&v)[8], const Pre& p) const {
;         const float r = p.r;
; #pragma unroll
;         for (int i = 0; i < 8; ++i) v[i] *= r;
.LBB0_458:
	s_or_b64 exec, exec, s[2:3]
	v_lshlrev_b64 v[52:53], 11, v[80:81]
	s_and_b64 s[100:101], s[44:45], s[46:47]
	s_cbranch_scc0 .Lp1w3_4
	s_waitcnt vmcnt(7)
	s_branch .Lp1wj_4

;     __device__ __forceinline__ float apply(int row, int col, float (&v)[8], const Pre& p) const {
;         const float r = p.r;
; #pragma unroll
;         for (int i = 0; i < 8; ++i) v[i] *= r;
;         const int reg = col >> 10, c = col & 1023;
;         bf16* dst;
;         if (reg < 2) {
;             if ((c & 127) < 32) {
; #pragma unroll
;                 for (int i = 0; i < 4; ++i) { const float x1 = v[i], x2 = v[4 + i]; v[i] = x1 * p.cs[i] - x2 * p.sn[i]; v[4 + i] = x2 * p.cs[i] + x1 * p.sn[i]; }
;             }
;             if (reg == 0) {
; #pragma unroll
;                 for (int i = 0; i < 8; ++i) v[i] *= QSCALE;
;             }
;             dst = (reg == 0 ? Q : K) + (size_t)row * 1024 + c;
;         } else if (reg == 2) dst = V + (size_t)row * 1024 + c;
;         else dst = U + ((size_t)(c >> 4) * S + row) * 16 + (c & 15);
.Lp1wj_4:
	v_pk_mul_f32 v[54:55], v[36:37], v[82:83] op_sel_hi:[1,0]
	v_pk_mul_f32 v[32:33], v[32:33], v[82:83] op_sel_hi:[1,0]
	v_pk_mul_f32 v[36:37], v[38:39], v[82:83] op_sel_hi:[1,0]
	v_pk_mul_f32 v[34:35], v[34:35], v[82:83] op_sel_hi:[1,0]
	s_and_b64 vcc, exec, s[10:11]
	s_mov_b64 s[2:3], -1
	s_cbranch_vccnz .LBB0_464
	s_and_b64 vcc, exec, s[8:9]
	s_cbranch_vccnz .LBB0_461
	v_lshlrev_b32_e32 v38, 10, v207
	v_and_b32_e32 v168, 0xdc000, v38
	v_lshl_add_u64 v[38:39], v[168:169], 0, v[80:81]
	v_lshlrev_b64 v[38:39], 5, v[38:39]
	v_lshl_add_u64 v[38:39], s[86:87], 0, v[38:39]
	v_mov_b32_e32 v168, v203
	s_cbranch_execz .LBB0_462
	s_branch .LBB0_463

; #define LAS __attribute__((address_space(3)))
; __device__ __forceinline__ unsigned pk2(float lo, float hi) { f32x2_t v = {lo, hi}; bf16x2_t b = __builtin_convertvector(v, bf16x2_t); return __builtin_bit_cast(unsigned, b); }
; __device__ __forceinline__ float bflo(unsigned w) { return __uint_as_float(w << 16); }
; __device__ __forceinline__ float bfhi(unsigned w) { return __uint_as_float(w & 0xffff0000u); }
; __device__ __forceinline__ void s5_out_block2(LAS unsigned char* lds, const bf16* __restrict__ MLAG, const bf16* __restrict__ WC, const bf16* __restrict__ HP, const bf16* __restrict__ U, ...
;     ...
;             const int kend = 2 * jj + 2;
; #pragma unroll 2
;             for (int ks = 0; ks < kend; ++ks) {
;                 const bf16x8 bv = *(const LAS bf16x8*)(ul + 32 * ks);
;                 const int tau = 2 * jj + rj - ks; const int tc = tau < 0 ? 0 : tau;
;                 bf16x8 av = *(const LAS bf16x8*)(ml + tc * 512); if (tau < 0) av = (bf16x8){0, 0, 0, 0, 0, 0, 0, 0};
;                 acc = __builtin_amdgcn_mfma_f32_32x32x16_bf16(av, bv, acc, 0, 0, 0);
;             }
;             const int c = ct * 32 + r;
; #pragma unroll
;             for (int ep = 0; ep < 2; ++ep) {
;                 const int j = 2 * jj + ep, t = c * 32 + j;
;                 unsigned pk[2][2];
; #pragma unroll
;                 for (int q2 = 0; q2 < 2; ++q2) {
;                     const int eg = 2 * ep + q2, p0 = 8 * q2 + 4 * h;
;                     const u32x2 uw = *(const LAS u32x2*)(lds + UOFF + r * UROW + j * 32 + p0 * 2);
;                     const f32x4 d = q2 ? dB : dA;
;                     const float y0 = gelu_tanh(acc[4 * eg + 0] + d[0] * bflo(uw.x)), y1 = gelu_tanh(acc[4 * eg + 1] + d[1] * bfhi(uw.x));
;                     const float y2 = gelu_tanh(acc[4 * eg + 2] + d[2] * bflo(uw.y)), y3 = gelu_tanh(acc[4 * eg + 3] + d[3] * bfhi(uw.y));
;                     pk[q2][0] = pk2(y0, y1); pk[q2][1] = pk2(y2, y3);
.LBB0_808:
	v_add_u32_e32 v220, s24, v160
	s_lshr_b32 s27, s24, 1
	v_lshl_add_u32 v220, v220, 9, v161
	v_mov_b32_e32 v221, v20
	v_cmp_lt_i32_e64 s[34:35], 0, v160
	v_add_u32_e32 v222, 0xfffffe00, v220
	v_max_i32_e32 v222, v222, v161
	ds_read_b128 v[188:191], v220
	ds_read_b128 v[192:195], v221
	ds_read_b128 v[196:199], v221 offset:32
	ds_read_b128 v[200:203], v222
	v_add_u32_e32 v220, 0xfffffc00, v220
	v_add_u32_e32 v221, 64, v221
	v_add_u32_e32 v222, 0xfffffe00, v220
	v_max_i32_e32 v222, v222, v161
.Ltz1_loop:
	s_cmp_eq_u32 s27, 0
	s_cbranch_scc1 .Ltz1_lastA
	ds_read_b128 v[204:207], v220
	ds_read_b128 v[208:211], v221
	ds_read_b128 v[212:215], v221 offset:32
	ds_read_b128 v[216:219], v222
	v_add_u32_e32 v220, 0xfffffc00, v220
	v_add_u32_e32 v221, 64, v221
	v_add_u32_e32 v222, 0xfffffe00, v220
	v_max_i32_e32 v222, v222, v161
	s_waitcnt lgkmcnt(4)
	v_mfma_f32_32x32x16_bf16 v[0:15], v[188:191], v[192:195], v[0:15]
	v_mfma_f32_32x32x16_bf16 v[0:15], v[200:203], v[196:199], v[0:15]
	s_add_i32 s27, s27, -1
	s_cmp_eq_u32 s27, 0
	s_cbranch_scc1 .Ltz1_lastB
	ds_read_b128 v[188:191], v220
	ds_read_b128 v[192:195], v221
	ds_read_b128 v[196:199], v221 offset:32
	ds_read_b128 v[200:203], v222
	v_add_u32_e32 v220, 0xfffffc00, v220
	v_add_u32_e32 v221, 64, v221
	v_add_u32_e32 v222, 0xfffffe00, v220
	v_max_i32_e32 v222, v222, v161
	s_waitcnt lgkmcnt(4)
	v_mfma_f32_32x32x16_bf16 v[0:15], v[204:207], v[208:211], v[0:15]
	v_mfma_f32_32x32x16_bf16 v[0:15], v[216:219], v[212:215], v[0:15]
	s_add_i32 s27, s27, -1
	s_branch .Ltz1_loop
.Ltz1_lastA:
	s_waitcnt lgkmcnt(0)
	v_cndmask_b32_e64 v200, 0, v200, s[34:35]
	v_cndmask_b32_e64 v201, 0, v201, s[34:35]
	v_cndmask_b32_e64 v202, 0, v202, s[34:35]
	v_cndmask_b32_e64 v203, 0, v203, s[34:35]
	v_mfma_f32_32x32x16_bf16 v[0:15], v[188:191], v[192:195], v[0:15]
	s_nop 0
	v_mfma_f32_32x32x16_bf16 v[0:15], v[200:203], v[196:199], v[0:15]
	s_branch .Ltz1_done
.Ltz1_lastB:
	s_waitcnt lgkmcnt(0)
	v_cndmask_b32_e64 v216, 0, v216, s[34:35]
	v_cndmask_b32_e64 v217, 0, v217, s[34:35]
	v_cndmask_b32_e64 v218, 0, v218, s[34:35]
	v_cndmask_b32_e64 v219, 0, v219, s[34:35]
	v_mfma_f32_32x32x16_bf16 v[0:15], v[204:207], v[208:211], v[0:15]
	s_nop 0
	v_mfma_f32_32x32x16_bf16 v[0:15], v[216:219], v[212:215], v[0:15]
.Ltz1_done:
	v_add_u32_e32 v20, s16, v163
	v_add_u32_e32 v20, 0x4000, v20
	ds_read2_b64 v[20:23], v20 offset1:2
	s_andn2_b64 vcc, exec, s[6:7]
	s_waitcnt lgkmcnt(0)
	v_lshlrev_b32_e32 v24, 16, v20
	v_and_b32_e32 v25, 0xffff0000, v20
	s_nop 3
	v_pk_fma_f32 v[24:25], v[32:33], v[24:25], v[0:1]
	s_nop 0
	v_mul_f32_e32 v0, 0x3d372713, v24
	v_mul_f32_e32 v0, v24, v0
	v_fma_f32 v0, v24, v0, v24
	v_mul_f32_e32 v1, 0x3d372713, v25
	v_mul_f32_e32 v0, 0x3f4c422a, v0
	v_mul_f32_e32 v1, v25, v1
	v_add_f32_e32 v0, v0, v0
	v_fma_f32 v1, v25, v1, v25
	v_mul_f32_e32 v0, 0x3fb8aa3b, v0
	v_exp_f32_e32 v20, v0
	v_mul_f32_e32 v0, 0x3f4c422a, v1
	v_add_f32_e32 v0, v0, v0
	v_mul_f32_e32 v0, 0x3fb8aa3b, v0
	v_exp_f32_e32 v1, v0
	v_add_f32_e32 v20, 1.0, v20
	v_rcp_f32_e32 v26, v20
	v_lshlrev_b32_e32 v20, 16, v21
	v_and_b32_e32 v21, 0xffff0000, v21
	v_add_f32_e32 v1, 1.0, v1
	v_pk_fma_f32 v[2:3], v[34:35], v[20:21], v[2:3]
	v_rcp_f32_e32 v27, v1
	v_mul_f32_e32 v1, 0x3d372713, v2
	v_mul_f32_e32 v1, v2, v1
	v_mul_f32_e32 v20, 0x3d372713, v3
	v_fma_f32 v1, v2, v1, v2
	v_mul_f32_e32 v20, v3, v20
	v_mul_f32_e32 v1, 0x3f4c422a, v1
	v_fma_f32 v20, v3, v20, v3
	v_add_f32_e32 v1, v1, v1
	v_mul_f32_e32 v20, 0x3f4c422a, v20
	v_mul_f32_e32 v1, 0x3fb8aa3b, v1
	v_add_f32_e32 v20, v20, v20
	v_exp_f32_e32 v1, v1
	v_mul_f32_e32 v20, 0x3fb8aa3b, v20
	v_exp_f32_e32 v28, v20
	v_pk_fma_f32 v[20:21], v[26:27], 2.0, 1.0 op_sel_hi:[1,0,0] neg_lo:[1,0,0] neg_hi:[1,0,0]
	v_add_f32_e32 v1, 1.0, v1
	v_rcp_f32_e32 v26, v1
	v_add_f32_e32 v1, 1.0, v28
	v_rcp_f32_e32 v27, v1
	v_pk_mul_f32 v[24:25], v[24:25], 0.5 op_sel_hi:[1,0]
	v_pk_add_f32 v[20:21], v[20:21], 1.0 op_sel_hi:[1,0]
	v_pk_mul_f32 v[2:3], v[2:3], 0.5 op_sel_hi:[1,0]
	v_pk_mul_f32 v[20:21], v[24:25], v[20:21]
	v_pk_fma_f32 v[24:25], v[26:27], 2.0, 1.0 op_sel_hi:[1,0,0] neg_lo:[1,0,0] neg_hi:[1,0,0]
	v_lshl_or_b32 v0, s23, 10, v162
	v_pk_add_f32 v[24:25], v[24:25], 1.0 op_sel_hi:[1,0]
	v_add_u32_e32 v152, s14, v0
	v_pk_mul_f32 v[24:25], v[2:3], v[24:25]
	v_cvt_pk_bf16_f32 v2, v20, v21
	v_lshlrev_b32_e32 v20, 16, v22
	v_and_b32_e32 v21, 0xffff0000, v22
	v_pk_fma_f32 v[4:5], v[36:37], v[20:21], v[4:5]
	v_lshlrev_b32_e32 v22, 16, v23
	v_mul_f32_e32 v1, 0x3d372713, v4
	v_mul_f32_e32 v1, v4, v1
	v_mul_f32_e32 v3, 0x3d372713, v5
	v_fma_f32 v1, v4, v1, v4
	v_mul_f32_e32 v3, v5, v3
	v_mul_f32_e32 v1, 0x3f4c422a, v1
	v_fma_f32 v3, v5, v3, v5
	v_add_f32_e32 v1, v1, v1
	v_mul_f32_e32 v3, 0x3f4c422a, v3
	v_mul_f32_e32 v1, 0x3fb8aa3b, v1
	v_add_f32_e32 v3, v3, v3
	v_exp_f32_e32 v1, v1
	v_mul_f32_e32 v3, 0x3fb8aa3b, v3
	v_exp_f32_e32 v21, v3
	v_and_b32_e32 v23, 0xffff0000, v23
	v_add_f32_e32 v1, 1.0, v1
	v_rcp_f32_e32 v20, v1
	v_add_f32_e32 v1, 1.0, v21
	v_pk_fma_f32 v[6:7], v[38:39], v[22:23], v[6:7]
	v_rcp_f32_e32 v21, v1
	v_mul_f32_e32 v1, 0x3d372713, v6
	v_mul_f32_e32 v1, v6, v1
	v_mul_f32_e32 v22, 0x3d372713, v7
	v_fma_f32 v1, v6, v1, v6
	v_mul_f32_e32 v22, v7, v22
	v_mul_f32_e32 v1, 0x3f4c422a, v1
	v_fma_f32 v22, v7, v22, v7
	v_add_f32_e32 v1, v1, v1
	v_mul_f32_e32 v22, 0x3f4c422a, v22
	v_mul_f32_e32 v1, 0x3fb8aa3b, v1
	v_add_f32_e32 v22, v22, v22
	v_exp_f32_e32 v1, v1
	v_mul_f32_e32 v22, 0x3fb8aa3b, v22
	v_exp_f32_e32 v23, v22
	v_pk_fma_f32 v[20:21], v[20:21], 2.0, 1.0 op_sel_hi:[1,0,0] neg_lo:[1,0,0] neg_hi:[1,0,0]
	v_add_f32_e32 v1, 1.0, v1
	v_rcp_f32_e32 v22, v1
	v_add_f32_e32 v1, 1.0, v23
	v_rcp_f32_e32 v23, v1
	v_add_u32_e32 v1, s17, v163
	v_add_u32_e32 v1, 0x4000, v1
	ds_read2_b64 v[172:175], v1 offset1:2
	v_pk_mul_f32 v[4:5], v[4:5], 0.5 op_sel_hi:[1,0]
	v_pk_add_f32 v[20:21], v[20:21], 1.0 op_sel_hi:[1,0]
	v_pk_mul_f32 v[6:7], v[6:7], 0.5 op_sel_hi:[1,0]
	v_pk_mul_f32 v[4:5], v[4:5], v[20:21]
	v_pk_fma_f32 v[20:21], v[22:23], 2.0, 1.0 op_sel_hi:[1,0,0] neg_lo:[1,0,0] neg_hi:[1,0,0]
	v_cvt_pk_bf16_f32 v3, v24, v25
	v_pk_add_f32 v[20:21], v[20:21], 1.0 op_sel_hi:[1,0]
	v_cvt_pk_bf16_f32 v4, v4, v5
	v_pk_mul_f32 v[6:7], v[6:7], v[20:21]
	s_waitcnt lgkmcnt(0)
; #define LAS __attribute__((address_space(3)))
; __device__ __forceinline__ unsigned pk2(float lo, float hi) { f32x2_t v = {lo, hi}; bf16x2_t b = __builtin_convertvector(v, bf16x2_t); return __builtin_bit_cast(unsigned, b); }
; __device__ __forceinline__ float bflo(unsigned w) { return __uint_as_float(w << 16); }
; __device__ __forceinline__ float bfhi(unsigned w) { return __uint_as_float(w & 0xffff0000u); }
; __device__ __forceinline__ void s5_out_block2(LAS unsigned char* lds, const bf16* __restrict__ MLAG, const bf16* __restrict__ WC, const bf16* __restrict__ HP, const bf16* __restrict__ U, ...
;     ...
;             for (int ks = 0; ks < 8; ++ks) { const bf16x8 bv = *(const LAS bf16x8*)(hl + 32 * ks); acc = __builtin_amdgcn_mfma_f32_32x32x16_bf16(wc[q][ks], bv, acc, 0, 0, 0); }
;     ...
;             const int c = ct * 32 + r;
; #pragma unroll
;             for (int ep = 0; ep < 2; ++ep) {
;                 const int j = 2 * jj + ep, t = c * 32 + j;
;                 unsigned pk[2][2];
; #pragma unroll
;                 for (int q2 = 0; q2 < 2; ++q2) {
;                     const int eg = 2 * ep + q2, p0 = 8 * q2 + 4 * h;
;                     const u32x2 uw = *(const LAS u32x2*)(lds + UOFF + r * UROW + j * 32 + p0 * 2);
;                     const f32x4 d = q2 ? dB : dA;
;                     const float y0 = gelu_tanh(acc[4 * eg + 0] + d[0] * bflo(uw.x)), y1 = gelu_tanh(acc[4 * eg + 1] + d[1] * bfhi(uw.x));
;                     const float y2 = gelu_tanh(acc[4 * eg + 2] + d[2] * bflo(uw.y)), y3 = gelu_tanh(acc[4 * eg + 3] + d[3] * bfhi(uw.y));
;                     pk[q2][0] = pk2(y0, y1); pk[q2][1] = pk2(y2, y3);
;                 }
;                 { auto rx = __builtin_amdgcn_permlane32_swap(pk[0][0], pk[1][0], false, false); pk[0][0] = rx[0]; pk[1][0] = rx[1]; }
;                 { auto ry = __builtin_amdgcn_permlane32_swap(pk[0][1], pk[1][1], false, false); pk[0][1] = ry[0]; pk[1][1] = ry[1]; }
;                 u32x4 o = {pk[0][0], pk[0][1], pk[1][0], pk[1][1]};
;                 *(u32x4*)(Y + (size_t)t * 1024 + g * 16 + 8 * h) = o;
	v_lshlrev_b32_e32 v20, 16, v172
	v_and_b32_e32 v21, 0xffff0000, v172
	v_pk_fma_f32 v[8:9], v[32:33], v[20:21], v[8:9]
	v_cvt_pk_bf16_f32 v5, v6, v7
	v_mul_f32_e32 v1, 0x3d372713, v8
	v_mul_f32_e32 v1, v8, v1
	v_mul_f32_e32 v20, 0x3d372713, v9
	v_fma_f32 v1, v8, v1, v8
	v_mul_f32_e32 v20, v9, v20
	v_mul_f32_e32 v1, 0x3f4c422a, v1
	v_fma_f32 v20, v9, v20, v9
	v_add_f32_e32 v1, v1, v1
	v_mul_f32_e32 v20, 0x3f4c422a, v20
	v_mul_f32_e32 v1, 0x3fb8aa3b, v1
	v_add_f32_e32 v20, v20, v20
	v_exp_f32_e32 v1, v1
	v_mul_f32_e32 v20, 0x3fb8aa3b, v20
	v_exp_f32_e32 v20, v20
	v_lshlrev_b64 v[6:7], 11, v[152:153]
	v_permlane32_swap_b32_e32 v2, v4
	v_permlane32_swap_b32_e32 v3, v5
	v_lshl_add_u64 v[6:7], v[156:157], 0, v[6:7]
	v_add_f32_e32 v1, 1.0, v1
	global_store_dwordx4 v[6:7], v[2:5], off
	v_pk_mul_f32 v[8:9], v[8:9], 0.5 op_sel_hi:[1,0]
	v_add_u32_e32 v152, s15, v0
	v_rcp_f32_e32 v2, v1
	v_add_f32_e32 v1, 1.0, v20
	v_mfma_f32_32x32x16_bf16 v[16:31], v[72:75], v[16:19], 0
	v_lshlrev_b32_e32 v4, 16, v173
	v_and_b32_e32 v5, 0xffff0000, v173
	v_fma_f32 v4, v34, v4, v10
	v_fma_f32 v5, v35, v5, v11
	v_rcp_f32_e32 v3, v1
	v_mul_f32_e32 v1, 0x3d372713, v4
	v_mul_f32_e32 v1, v4, v1
	v_mul_f32_e32 v6, 0x3d372713, v5
	v_mfma_f32_32x32x16_bf16 v[16:31], v[76:79], v[148:151], v[16:31]
	v_fma_f32 v1, v4, v1, v4
	v_mul_f32_e32 v6, v5, v6
	v_mul_f32_e32 v1, 0x3f4c422a, v1
	v_fma_f32 v6, v5, v6, v5
	v_add_f32_e32 v1, v1, v1
	v_mul_f32_e32 v6, 0x3f4c422a, v6
	v_mul_f32_e32 v1, 0x3fb8aa3b, v1
	v_mfma_f32_32x32x16_bf16 v[16:31], v[80:83], v[144:147], v[16:31]
	v_add_f32_e32 v6, v6, v6
	v_exp_f32_e32 v1, v1
	v_mul_f32_e32 v6, 0x3fb8aa3b, v6
	v_exp_f32_e32 v7, v6
	v_pk_fma_f32 v[2:3], v[2:3], 2.0, 1.0 op_sel_hi:[1,0,0] neg_lo:[1,0,0] neg_hi:[1,0,0]
	v_add_f32_e32 v1, 1.0, v1
	v_pk_add_f32 v[2:3], v[2:3], 1.0 op_sel_hi:[1,0]
	v_mfma_f32_32x32x16_bf16 v[16:31], v[84:87], v[140:143], v[16:31]
	v_mul_f32_e64 v2, v8, v2
	v_mul_f32_e64 v3, v9, v3
	v_lshlrev_b32_e32 v8, 16, v174
	v_and_b32_e32 v9, 0xffff0000, v174
	v_rcp_f32_e32 v6, v1
	v_add_f32_e32 v1, 1.0, v7
	v_pk_fma_f32 v[8:9], v[36:37], v[8:9], v[12:13]
	v_rcp_f32_e32 v7, v1
	v_mul_f32_e32 v1, 0x3d372713, v8
	v_mul_f32_e32 v1, v8, v1
	v_mul_f32_e32 v10, 0x3d372713, v9
	v_fma_f32 v1, v8, v1, v8
	v_mul_f32_e32 v10, v9, v10
	v_mul_f32_e32 v1, 0x3f4c422a, v1
	v_fma_f32 v10, v9, v10, v9
	v_add_f32_e32 v1, v1, v1
	v_mul_f32_e32 v10, 0x3f4c422a, v10
	v_mfma_f32_32x32x16_bf16 v[16:31], v[88:91], v[136:139], v[16:31]
	v_mul_f32_e32 v1, 0x3fb8aa3b, v1
	v_add_f32_e32 v10, v10, v10
	v_exp_f32_e32 v1, v1
	v_mul_f32_e32 v10, 0x3fb8aa3b, v10
	v_exp_f32_e32 v11, v10
	v_pk_fma_f32 v[6:7], v[6:7], 2.0, 1.0 op_sel_hi:[1,0,0] neg_lo:[1,0,0] neg_hi:[1,0,0]
	v_add_f32_e32 v1, 1.0, v1
	v_rcp_f32_e32 v10, v1
	v_add_f32_e32 v1, 1.0, v11
	v_pk_mul_f32 v[4:5], v[4:5], 0.5 op_sel_hi:[1,0]
	v_pk_add_f32 v[6:7], v[6:7], 1.0 op_sel_hi:[1,0]
	v_rcp_f32_e32 v11, v1
	v_mfma_f32_32x32x16_bf16 v[16:31], v[92:95], v[132:135], v[16:31]
	v_mul_f32_e64 v4, v4, v6
	v_mul_f32_e64 v5, v5, v7
	v_lshlrev_b32_e32 v6, 16, v175
	v_and_b32_e32 v7, 0xffff0000, v175
	v_fma_f32 v6, v38, v6, v14
	v_fma_f32 v7, v39, v7, v15
	v_cvt_pk_bf16_f32 v2, v2, v3
	v_mul_f32_e32 v1, 0x3d372713, v6
	v_cvt_pk_bf16_f32 v3, v4, v5
	v_pk_fma_f32 v[4:5], v[10:11], 2.0, 1.0 op_sel_hi:[1,0,0] neg_lo:[1,0,0] neg_hi:[1,0,0]
	v_mul_f32_e32 v1, v6, v1
	v_mul_f32_e32 v10, 0x3d372713, v7
	v_fma_f32 v1, v6, v1, v6
	v_mul_f32_e32 v10, v7, v10
	v_mul_f32_e32 v1, 0x3f4c422a, v1
	v_fma_f32 v10, v7, v10, v7
	v_add_f32_e32 v1, v1, v1
	v_mul_f32_e32 v10, 0x3f4c422a, v10
	v_mul_f32_e32 v1, 0x3fb8aa3b, v1
	v_add_f32_e32 v10, v10, v10
	v_mfma_f32_32x32x16_bf16 v[16:31], v[96:99], v[128:131], v[16:31]
	v_exp_f32_e32 v1, v1
	v_mul_f32_e32 v10, 0x3fb8aa3b, v10
	v_exp_f32_e32 v11, v10
	v_pk_mul_f32 v[8:9], v[8:9], 0.5 op_sel_hi:[1,0]
	v_add_f32_e32 v1, 1.0, v1
	v_rcp_f32_e32 v10, v1
	v_add_f32_e32 v1, 1.0, v11
	v_rcp_f32_e32 v11, v1
	v_mfma_f32_32x32x16_bf16 v[16:31], v[100:103], v[124:127], v[16:31]
	v_add_f32_e64 v4, v4, 1.0
	v_add_f32_e64 v5, v5, 1.0
	v_mul_f32_e64 v6, v6, 0.5
	v_mul_f32_e64 v7, v7, 0.5
	v_mul_f32_e64 v4, v8, v4
	v_mul_f32_e64 v5, v9, v5
	v_pk_fma_f32 v[8:9], v[10:11], 2.0, 1.0 op_sel_hi:[1,0,0] neg_lo:[1,0,0] neg_hi:[1,0,0]
	v_cvt_pk_bf16_f32 v4, v4, v5
	v_pk_add_f32 v[8:9], v[8:9], 1.0 op_sel_hi:[1,0]
	s_nop 0
	v_permlane32_swap_b32_e32 v2, v4
	v_pk_mul_f32 v[6:7], v[6:7], v[8:9]
	v_mov_b32_e32 v1, v164
	v_cvt_pk_bf16_f32 v5, v6, v7
	v_lshlrev_b64 v[6:7], 11, v[152:153]
	s_nop 0
	v_permlane32_swap_b32_e32 v3, v5
	v_lshl_add_u64 v[6:7], v[156:157], 0, v[6:7]
	s_mov_b32 s23, s22
	global_store_dwordx4 v[6:7], v[2:5], off
	s_cbranch_vccnz .LBB0_804
; #define LAS __attribute__((address_space(3)))
; __device__ __forceinline__ void xcd_barrier(const XcdBarrier& b) {
;     asm volatile("s_waitcnt vmcnt(0)" ::: "memory");
;     __syncthreads();
;     if (threadIdx.x == 0) {
;         unsigned* bar = b.bar;
;         __builtin_amdgcn_s_waitcnt(0);
;         unsigned nloc = b.st[0], nx = b.st[1];
;         if (nloc == 0u) { xcd_barrier_complete(bar, b.x, nloc, nx); b.st[0] = nloc; b.st[1] = nx; }
; __device__ __forceinline__ void s5_out_block2(LAS unsigned char* lds, const bf16* __restrict__ MLAG, const bf16* __restrict__ WC, const bf16* __restrict__ HP, const bf16* __restrict__ U, ...
;     ...
;             const int kend = 2 * jj + 2;
; #pragma unroll 2
;             for (int ks = 0; ks < kend; ++ks) {
;                 const bf16x8 bv = *(const LAS bf16x8*)(ul + 32 * ks);
;                 const int tau = 2 * jj + rj - ks; const int tc = tau < 0 ? 0 : tau;
;                 bf16x8 av = *(const LAS bf16x8*)(ml + tc * 512); if (tau < 0) av = (bf16x8){0, 0, 0, 0, 0, 0, 0, 0};
;                 acc = __builtin_amdgcn_mfma_f32_32x32x16_bf16(av, bv, acc, 0, 0, 0);
;             }
.LBB0_810:
	s_add_i32 s27, s23, 1
	v_add_u32_e32 v220, s27, v160
	s_lshr_b32 s27, s27, 1
	v_lshl_add_u32 v220, v220, 9, v161
	v_mov_b32_e32 v221, v1
	v_cmp_lt_i32_e64 s[34:35], 0, v160
	v_add_u32_e32 v222, 0xfffffe00, v220
	v_max_i32_e32 v222, v222, v161
	ds_read_b128 v[188:191], v220
	ds_read_b128 v[192:195], v221
	ds_read_b128 v[196:199], v221 offset:32
	ds_read_b128 v[200:203], v222
	v_add_u32_e32 v220, 0xfffffc00, v220
	v_add_u32_e32 v221, 64, v221
	v_add_u32_e32 v222, 0xfffffe00, v220
	v_max_i32_e32 v222, v222, v161
.Ltz2_loop:
	s_cmp_eq_u32 s27, 0
	s_cbranch_scc1 .Ltz2_lastA
	ds_read_b128 v[204:207], v220
	ds_read_b128 v[208:211], v221
	ds_read_b128 v[212:215], v221 offset:32
	ds_read_b128 v[216:219], v222
	v_add_u32_e32 v220, 0xfffffc00, v220
	v_add_u32_e32 v221, 64, v221
	v_add_u32_e32 v222, 0xfffffe00, v220
	v_max_i32_e32 v222, v222, v161
	s_waitcnt lgkmcnt(4)
	v_mfma_f32_32x32x16_bf16 v[16:31], v[188:191], v[192:195], v[16:31]
	v_mfma_f32_32x32x16_bf16 v[16:31], v[200:203], v[196:199], v[16:31]
	s_add_i32 s27, s27, -1
	s_cmp_eq_u32 s27, 0
	s_cbranch_scc1 .Ltz2_lastB
	ds_read_b128 v[188:191], v220
	ds_read_b128 v[192:195], v221
	ds_read_b128 v[196:199], v221 offset:32
	ds_read_b128 v[200:203], v222
	v_add_u32_e32 v220, 0xfffffc00, v220
	v_add_u32_e32 v221, 64, v221
	v_add_u32_e32 v222, 0xfffffe00, v220
	v_max_i32_e32 v222, v222, v161
	s_waitcnt lgkmcnt(4)
	v_mfma_f32_32x32x16_bf16 v[16:31], v[204:207], v[208:211], v[16:31]
	v_mfma_f32_32x32x16_bf16 v[16:31], v[216:219], v[212:215], v[16:31]
	s_add_i32 s27, s27, -1
	s_branch .Ltz2_loop
.Ltz2_lastA:
	s_waitcnt lgkmcnt(0)
	v_cndmask_b32_e64 v200, 0, v200, s[34:35]
	v_cndmask_b32_e64 v201, 0, v201, s[34:35]
	v_cndmask_b32_e64 v202, 0, v202, s[34:35]
	v_cndmask_b32_e64 v203, 0, v203, s[34:35]
	v_mfma_f32_32x32x16_bf16 v[16:31], v[188:191], v[192:195], v[16:31]
	s_nop 0
	v_mfma_f32_32x32x16_bf16 v[16:31], v[200:203], v[196:199], v[16:31]
	s_branch .Ltz2_done
.Ltz2_lastB:
	s_waitcnt lgkmcnt(0)
	v_cndmask_b32_e64 v216, 0, v216, s[34:35]
	v_cndmask_b32_e64 v217, 0, v217, s[34:35]
	v_cndmask_b32_e64 v218, 0, v218, s[34:35]
	v_cndmask_b32_e64 v219, 0, v219, s[34:35]
	v_mfma_f32_32x32x16_bf16 v[16:31], v[204:207], v[208:211], v[16:31]
	s_nop 0
	v_mfma_f32_32x32x16_bf16 v[16:31], v[216:219], v[212:215], v[16:31]
.Ltz2_done:
	s_branch .LBB0_804
.LBB0_811:
	s_cmp_lt_i32 s90, 5
	s_cselect_b64 s[2:3], -1, 0
	s_cmp_gt_i32 s91, 5
	v_readlane_b32 s52, v245, 9
	s_cselect_b64 s[0:1], -1, 0
	v_readlane_b32 s53, v245, 10
	v_readlane_b32 s54, v245, 11
	v_readlane_b32 s55, v245, 12
	s_and_b64 s[2:3], s[2:3], s[0:1]
	v_readlane_b32 s60, v245, 7
	v_readlane_b32 s62, v245, 28
	v_readlane_b32 s64, v245, 26
	v_readlane_b32 s52, v245, 24
	v_readlane_b32 s54, v245, 22
	s_andn2_b64 vcc, exec, s[2:3]
	v_readlane_b32 s56, v245, 13
	v_readlane_b32 s57, v245, 14
	v_readlane_b32 s58, v245, 15
	v_readlane_b32 s59, v245, 16
	v_readlane_b32 s61, v245, 8
	v_readlane_b32 s63, v245, 29
	v_readlane_b32 s65, v245, 27
	v_readlane_b32 s53, v245, 25
	v_readlane_b32 s55, v245, 23
	s_cbranch_vccnz .LBB0_865
	s_waitcnt vmcnt(0)
	s_barrier
	s_mov_b64 s[2:3], exec
	v_readlane_b32 s4, v245, 5
	v_readlane_b32 s5, v245, 6
	s_and_b64 s[4:5], s[2:3], s[4:5]
	s_mov_b64 exec, s[4:5]
	s_cbranch_execz .LBB0_864
	s_add_i32 s4, 0, 0x24000
	v_mov_b32_e32 v0, s4
	s_waitcnt vmcnt(0) expcnt(0) lgkmcnt(0)
	ds_read_b32 v2, v0
	s_add_i32 s4, 0, 0x24004
	v_mov_b32_e32 v0, s4
	ds_read_b32 v0, v0
	s_waitcnt lgkmcnt(1)
	v_cmp_ne_u32_e32 vcc, 0, v2
	s_cbranch_vccnz .LBB0_828
	v_readlane_b32 s4, v245, 0
	s_mul_i32 s33, s4, s60
	s_add_u32 s4, s88, 0x800200
	s_addc_u32 s5, s89, 0
	s_add_u32 s6, s88, 0x800400
	s_addc_u32 s7, s89, 0
	s_add_u32 s8, s88, 0x800500
	s_addc_u32 s9, s89, 0
	s_add_u32 s14, s88, 0x800600
	s_addc_u32 s15, s89, 0
	s_add_u32 s16, s88, 0x800700
	s_addc_u32 s17, s89, 0
	s_add_u32 s18, s88, 0x800800
	s_addc_u32 s19, s89, 0
	s_add_u32 s20, s88, 0x800900
	s_addc_u32 s21, s89, 0
	s_add_u32 s22, s88, 0x800a00
	s_addc_u32 s23, s89, 0
	s_add_u32 s24, s88, 0x800b00
	s_addc_u32 s25, s89, 0
	s_add_u32 s26, s88, 0x800c00
	s_addc_u32 s27, s89, 0
	s_add_u32 s28, s88, 0x800d00
	s_addc_u32 s29, s89, 0
	s_add_u32 s30, s88, 0x800e00
	s_addc_u32 s31, s89, 0
	s_add_u32 s34, s88, 0x800f00
	s_addc_u32 s35, s89, 0
	s_add_u32 s36, s88, 0x801000
	s_addc_u32 s37, s89, 0
	s_add_u32 s38, s88, 0x801100
	s_addc_u32 s39, s89, 0
	s_add_u32 s40, s88, 0x801200
	s_addc_u32 s41, s89, 0
	s_add_u32 s42, s88, 0x801300
	s_mul_i32 s33, s33, s61
	s_addc_u32 s43, s89, 0
	s_mov_b32 s50, 1
	v_mov_b32_e32 v16, 0
	s_branch .LBB0_816

; #define LAS __attribute__((address_space(3)))
; __global__ void __launch_bounds__(512, 2) mega(Args a) {
;     extern __shared__ __attribute__((aligned(16))) unsigned char lds_raw[];
;     LAS unsigned char* lds = (LAS unsigned char*)lds_raw;
;     const int tid = threadIdx.x, lane = tid & 63, wave = __builtin_amdgcn_readfirstlane(tid >> 6);
	.amdhsa_kernel _Z4mega4Args
		.amdhsa_group_segment_fixed_size 0
		.amdhsa_private_segment_fixed_size 0
		.amdhsa_kernarg_size 432
		.amdhsa_user_sgpr_count 2
		.amdhsa_user_sgpr_dispatch_ptr 0
		.amdhsa_user_sgpr_queue_ptr 0
		.amdhsa_user_sgpr_kernarg_segment_ptr 1
		.amdhsa_user_sgpr_dispatch_id 0
		.amdhsa_user_sgpr_kernarg_preload_length 0
		.amdhsa_user_sgpr_kernarg_preload_offset 0
		.amdhsa_user_sgpr_private_segment_size 0
		.amdhsa_uses_dynamic_stack 0
		.amdhsa_enable_private_segment 0
		.amdhsa_system_sgpr_workgroup_id_x 1
		.amdhsa_system_sgpr_workgroup_id_y 0
		.amdhsa_system_sgpr_workgroup_id_z 0
		.amdhsa_system_sgpr_workgroup_info 0
		.amdhsa_system_vgpr_workitem_id 2
		.amdhsa_next_free_vgpr 246
		.amdhsa_next_free_sgpr 102
		.amdhsa_accum_offset 248
		.amdhsa_reserve_vcc 1
		.amdhsa_float_round_mode_32 0
		.amdhsa_float_round_mode_16_64 0
		.amdhsa_float_denorm_mode_32 3
		.amdhsa_float_denorm_mode_16_64 3
		.amdhsa_dx10_clamp 1
		.amdhsa_ieee_mode 1
		.amdhsa_fp16_overflow 0
		.amdhsa_tg_split 0
		.amdhsa_exception_fp_ieee_invalid_op 0
		.amdhsa_exception_fp_denorm_src 0
		.amdhsa_exception_fp_ieee_div_zero 0
		.amdhsa_exception_fp_ieee_overflow 0
		.amdhsa_exception_fp_ieee_underflow 0
		.amdhsa_exception_fp_ieee_inexact 0
		.amdhsa_exception_int_div_zero 0
	.end_amdhsa_kernel

; #define LAS __attribute__((address_space(3)))
; __global__ void __launch_bounds__(512, 2) mega(Args a) {
;     extern __shared__ __attribute__((aligned(16))) unsigned char lds_raw[];
;     LAS unsigned char* lds = (LAS unsigned char*)lds_raw;
;     const int tid = threadIdx.x, lane = tid & 63, wave = __builtin_amdgcn_readfirstlane(tid >> 6);
amdhsa.kernels:
  - .agpr_count:     0
    .args:
      - .offset:         0
        .size:           176
        .value_kind:     by_value
      - .offset:         176
        .size:           4
        .value_kind:     hidden_block_count_x
      - .offset:         180
        .size:           4
        .value_kind:     hidden_block_count_y
      - .offset:         184
        .size:           4
        .value_kind:     hidden_block_count_z
      - .offset:         188
        .size:           2
        .value_kind:     hidden_group_size_x
      - .offset:         190
        .size:           2
        .value_kind:     hidden_group_size_y
      - .offset:         192
        .size:           2
        .value_kind:     hidden_group_size_z
      - .offset:         194
        .size:           2
        .value_kind:     hidden_remainder_x
      - .offset:         196
        .size:           2
        .value_kind:     hidden_remainder_y
      - .offset:         198
        .size:           2
        .value_kind:     hidden_remainder_z
      - .offset:         216
        .size:           8
        .value_kind:     hidden_global_offset_x
      - .offset:         224
        .size:           8
        .value_kind:     hidden_global_offset_y
      - .offset:         232
        .size:           8
        .value_kind:     hidden_global_offset_z
      - .offset:         240
        .size:           2
        .value_kind:     hidden_grid_dims
      - .offset:         264
        .size:           8
        .value_kind:     hidden_multigrid_sync_arg
      - .offset:         296
        .size:           4
        .value_kind:     hidden_dynamic_lds_size
    .group_segment_fixed_size: 0
    .kernarg_segment_align: 8
    .kernarg_segment_size: 432
    .language:       OpenCL C
    .language_version:
      - 2
      - 0
    .max_flat_workgroup_size: 512
    .name:           _Z4mega4Args
    .private_segment_fixed_size: 0
    .sgpr_count:     108
    .sgpr_spill_count: 54
    .symbol:         _Z4mega4Args.kd
    .uniform_work_group_size: 1
    .uses_dynamic_stack: false
    .vgpr_count:     246
    .vgpr_spill_count: 0
    .wavefront_size: 64
